# P3 decode-step iterations re-dealt: three mLSTM iterations on the 64 workgroups without passB, delta-rule pairs elsewhere
# speedup vs baseline: 1.0191x; 1.0034x over previous
.LBB0_553:
	v_writelane_b32 v238, s26, 27
	s_cmpk_lt_i32 s2, 0x220
	s_cselect_b64 s[4:5], -1, 0
	v_writelane_b32 v238, s27, 28
	v_writelane_b32 v238, s96, 29
	v_writelane_b32 v238, s4, 33
	s_cmpk_gt_i32 s2, 0x21f
	s_nop 0
	v_writelane_b32 v238, s5, 34
	s_cbranch_scc1 .LBB0_618
	s_add_u32 s12, s28, 0x90fe040
	s_addc_u32 s13, s29, 0
	s_add_u32 s20, s30, 0x10e00800
	s_addc_u32 s21, s31, 0
	s_add_u32 s22, s28, 0x50fe040
	s_addc_u32 s23, s29, 0
	s_add_u32 s24, s30, 0x10e00000
	v_mbcnt_lo_u32_b32 v0, -1, 0
	v_readlane_b32 s4, v238, 27
	s_addc_u32 s25, s31, 0
	s_mov_b32 s17, 0xa000
	s_movk_i32 s27, 0x2000
	v_mov_b32_e32 v17, 0
	s_movk_i32 s37, 0x3800
	s_movk_i32 s39, 0x3000
	v_mov_b32_e32 v177, 0x3ecc95a3
	s_movk_i32 s47, 0x1000
	s_movk_i32 s50, 0x4000
	s_movk_i32 s51, 0x5000
	s_movk_i32 s82, 0x6000
	s_movk_i32 s83, 0x7000
	s_mov_b32 s96, 0x8000
	s_mov_b32 s97, 0x9000
	s_mov_b32 s10, 0xb000
	s_mov_b32 s11, 0xc000
	s_mov_b32 s42, 0xd000
	s_mov_b32 s18, 0xe000
	s_mov_b32 s19, 0xf000
	s_mov_b32 s45, 0x1c000
	s_mov_b32 s46, 0x1d000
	s_mov_b32 s14, 0x1e000
	s_mov_b32 s26, 0x3b800000
	s_mov_b32 s36, 0x358637bd
	s_mov_b32 s43, 0x800000
	s_brev_b32 s38, 60
	v_mov_b32_e32 v184, 0x7f800000
	v_mov_b32_e32 v185, 0x7fc00000
	v_mov_b32_e32 v186, 0xff800000
	v_mbcnt_hi_u32_b32 v187, -1, v0
	v_mov_b32_e32 v18, 0x3f317218
	s_mov_b32 s44, s4
	s_mov_b32 s101, s16
	s_mov_b32 s100, 0x200
	v_readlane_b32 s5, v239, 2
	s_nop 0
	s_cmp_lg_u32 s5, 0x100
	s_cbranch_scc1 .Lsb_done
	s_cmp_lt_i32 s4, 64
	s_cbranch_scc1 .Lsb_a
	s_add_i32 s44, s4, 0xffffffc0
	s_mov_b32 s101, 0xa0
	s_mov_b32 s100, 0x100
	s_cmp_lt_i32 s4, 0xa0
	s_cbranch_scc1 .Lsb_done
	s_mov_b32 s101, 0x160
	s_mov_b32 s100, 0x200
	s_branch .Lsb_done
.Lsb_a:
	s_add_i32 s44, s4, 0x100
	s_mov_b32 s101, 64
	s_mov_b32 s100, 0x1c0
